# pool phase: per-token normalisation factor computed once per tile with one token per lane + lane broadcast (was recomputed by all lanes per token)
# speedup vs baseline: 1.0090x; 1.0029x over previous
; __device__ __forceinline__ unsigned pkbf(float lo, float hi) { unsigned r; asm volatile("v_cvt_pk_bf16_f32 %0, %1, %2" : "=v"(r) : "v"(lo), "v"(hi)); return r; }
; __device__ __forceinline__ void pool_phase(const Params& a, LAS unsigned char* lds) {
;     ...
; #pragma unroll
;         for (int tt = 0; tt < 32; ++tt) { const int tl = half * 32 + tt, t = t0 + tl;
;             const float f = sqrtf(ssa[t] * (1.0f / (NH * DV)) + EPS) / sqrtf(((ssl[tl] + ssl[64 + tl]) + (ssl[128 + tl] + ssl[192 + tl])) * (1.0f / POOLW) + EPS);
;             MX[(size_t)t * DM + 64 * g + d] = (bf16)(pkbf(o[tt] * f, 0.f) & 0xffffu); }
.LBB0_630:
	s_or_b64 exec, exec, s[2:3]
	s_add_i32 s8, s92, s16
	s_ashr_i32 s9, s8, 31
	s_lshl_b64 s[2:3], s[8:9], 2
	s_add_u32 s2, s10, s2
	s_addc_u32 s3, s11, s3
	s_waitcnt lgkmcnt(0)
	s_barrier
	v_mbcnt_lo_u32_b32 v151, -1, 0
	v_mbcnt_hi_u32_b32 v151, -1, v151
	v_and_b32_e32 v151, 31, v151
	v_lshlrev_b32_e32 v151, 2, v151
	global_load_dword v150, v151, s[2:3]
	v_add_u32_e32 v88, s13, v88
	s_waitcnt vmcnt(0)
	v_mov_b32_e32 v170, v150
	v_fmamk_f32 v170, v170, 0x3aaaaaab, v94
	v_cmp_gt_f32_e32 vcc, s90, v170
	v_mul_f32_e32 v171, 0x4f800000, v170
	s_nop 0
	v_cndmask_b32_e32 v170, v170, v171, vcc
	v_sqrt_f32_e32 v171, v170
	s_nop 0
	v_add_u32_e32 v172, -1, v171
	v_fma_f32 v173, -v172, v171, v170
	v_cmp_ge_f32_e64 s[2:3], 0, v173
	v_add_u32_e32 v173, 1, v171
	s_nop 0
	v_cndmask_b32_e64 v172, v171, v172, s[2:3]
	v_fma_f32 v171, -v173, v171, v170
	v_cmp_lt_f32_e64 s[2:3], 0, v171
	s_nop 1
	v_cndmask_b32_e64 v171, v172, v173, s[2:3]
	v_mul_f32_e32 v172, 0x37800000, v171
	v_readlane_b32 s2, v248, 20
	v_cndmask_b32_e32 v171, v171, v172, vcc
	v_cmp_class_f32_e32 vcc, v170, v95
	v_add_u32_e32 v173, s2, v151
	s_nop 0
	v_cndmask_b32_e32 v172, v171, v170, vcc
	ds_read2st64_b32 v[170:171], v173 offset1:1
	s_waitcnt lgkmcnt(0)
	v_add_f32_e32 v174, v170, v171
	ds_read2st64_b32 v[170:171], v173 offset0:2 offset1:3
	s_waitcnt lgkmcnt(0)
; __device__ __forceinline__ unsigned pkbf(float lo, float hi) { unsigned r; asm volatile("v_cvt_pk_bf16_f32 %0, %1, %2" : "=v"(r) : "v"(lo), "v"(hi)); return r; }
; __device__ __forceinline__ void pool_phase(const Params& a, LAS unsigned char* lds) {
;     ...
; #pragma unroll
;         for (int tt = 0; tt < 32; ++tt) { const int tl = half * 32 + tt, t = t0 + tl;
;             const float f = sqrtf(ssa[t] * (1.0f / (NH * DV)) + EPS) / sqrtf(((ssl[tl] + ssl[64 + tl]) + (ssl[128 + tl] + ssl[192 + tl])) * (1.0f / POOLW) + EPS);
;             MX[(size_t)t * DM + 64 * g + d] = (bf16)(pkbf(o[tt] * f, 0.f) & 0xffffu); }
	v_add_f32_e32 v170, v170, v171
	v_add_f32_e32 v170, v174, v170
	v_fmamk_f32 v170, v170, 0x3b800000, v94
	v_cmp_gt_f32_e32 vcc, s90, v170
	v_mul_f32_e32 v171, 0x4f800000, v170
	s_nop 0
	v_cndmask_b32_e32 v170, v170, v171, vcc
	v_sqrt_f32_e32 v171, v170
	s_nop 0
	v_add_u32_e32 v173, -1, v171
	v_fma_f32 v174, -v173, v171, v170
	v_cmp_ge_f32_e64 s[2:3], 0, v174
	v_add_u32_e32 v174, 1, v171
	s_nop 0
	v_cndmask_b32_e64 v173, v171, v173, s[2:3]
	v_fma_f32 v171, -v174, v171, v170
	v_cmp_lt_f32_e64 s[2:3], 0, v171
	s_nop 1
	v_cndmask_b32_e64 v171, v173, v174, s[2:3]
	v_mul_f32_e32 v173, 0x37800000, v171
	v_cndmask_b32_e32 v171, v171, v173, vcc
	v_cmp_class_f32_e32 vcc, v170, v95
	s_nop 1
	v_cndmask_b32_e32 v170, v171, v170, vcc
	v_div_scale_f32 v171, s[2:3], v170, v170, v172
	v_rcp_f32_e32 v173, v171
	s_nop 0
	s_nop 0
	s_nop 0
	v_fma_f32 v174, -v171, v173, 1.0
	v_fmac_f32_e32 v173, v174, v173
	v_div_scale_f32 v174, vcc, v172, v170, v172
	v_mul_f32_e32 v175, v174, v173
	v_fma_f32 v176, -v171, v175, v174
	v_fmac_f32_e32 v175, v176, v173
	v_fma_f32 v171, -v171, v175, v174
	v_div_fmas_f32 v171, v171, v173, v175
	v_div_fixup_f32 v170, v171, v170, v172
	s_add_i32 s8, s92, s16
	s_ashr_i32 s9, s8, 31
	s_lshl_b64 s[8:9], s[8:9], 11
	v_lshl_add_u64 v[172:173], v[4:5], 0, s[8:9]
	s_mov_b64 s[8:9], 0x1000
	v_readlane_b32 s2, v170, 0
	v_readlane_b32 s3, v170, 1
	s_nop 1
	v_mul_f32_e32 v119, s2, v119
	v_mul_f32_e32 v118, s3, v118
	v_cvt_pk_bf16_f32 v119, v119, v1
	v_cvt_pk_bf16_f32 v118, v118, v1
	global_store_short v[172:173], v119, off
	global_store_short v[172:173], v118, off offset:2048
	v_lshl_add_u64 v[172:173], v[172:173], 0, s[8:9]
	v_readlane_b32 s2, v170, 2
	v_readlane_b32 s3, v170, 3
	s_nop 1
	v_mul_f32_e32 v117, s2, v117
	v_mul_f32_e32 v116, s3, v116
	v_cvt_pk_bf16_f32 v117, v117, v1
	v_cvt_pk_bf16_f32 v116, v116, v1
	global_store_short v[172:173], v117, off
	global_store_short v[172:173], v116, off offset:2048
	v_lshl_add_u64 v[172:173], v[172:173], 0, s[8:9]
	v_readlane_b32 s2, v170, 4
	v_readlane_b32 s3, v170, 5
	s_nop 1
	v_mul_f32_e32 v115, s2, v115
	v_mul_f32_e32 v114, s3, v114
	v_cvt_pk_bf16_f32 v115, v115, v1
	v_cvt_pk_bf16_f32 v114, v114, v1
	global_store_short v[172:173], v115, off
	global_store_short v[172:173], v114, off offset:2048
	v_lshl_add_u64 v[172:173], v[172:173], 0, s[8:9]
	v_readlane_b32 s2, v170, 6
	v_readlane_b32 s3, v170, 7
	s_nop 1
	v_mul_f32_e32 v113, s2, v113
	v_mul_f32_e32 v112, s3, v112
	v_cvt_pk_bf16_f32 v113, v113, v1
	v_cvt_pk_bf16_f32 v112, v112, v1
	global_store_short v[172:173], v113, off
	global_store_short v[172:173], v112, off offset:2048
	v_lshl_add_u64 v[172:173], v[172:173], 0, s[8:9]
	v_readlane_b32 s2, v170, 8
	v_readlane_b32 s3, v170, 9
	s_nop 1
	v_mul_f32_e32 v111, s2, v111
	v_mul_f32_e32 v110, s3, v110
	v_cvt_pk_bf16_f32 v111, v111, v1
	v_cvt_pk_bf16_f32 v110, v110, v1
	global_store_short v[172:173], v111, off
	global_store_short v[172:173], v110, off offset:2048
	v_lshl_add_u64 v[172:173], v[172:173], 0, s[8:9]
	v_readlane_b32 s2, v170, 10
	v_readlane_b32 s3, v170, 11
	s_nop 1
	v_mul_f32_e32 v109, s2, v109
	v_mul_f32_e32 v108, s3, v108
	v_cvt_pk_bf16_f32 v109, v109, v1
	v_cvt_pk_bf16_f32 v108, v108, v1
	global_store_short v[172:173], v109, off
	global_store_short v[172:173], v108, off offset:2048
	v_lshl_add_u64 v[172:173], v[172:173], 0, s[8:9]
	v_readlane_b32 s2, v170, 12
	v_readlane_b32 s3, v170, 13
	s_nop 1
	v_mul_f32_e32 v107, s2, v107
	v_mul_f32_e32 v106, s3, v106
	v_cvt_pk_bf16_f32 v107, v107, v1
	v_cvt_pk_bf16_f32 v106, v106, v1
	global_store_short v[172:173], v107, off
	global_store_short v[172:173], v106, off offset:2048
	v_lshl_add_u64 v[172:173], v[172:173], 0, s[8:9]
	v_readlane_b32 s2, v170, 14
	v_readlane_b32 s3, v170, 15
	s_nop 1
	v_mul_f32_e32 v105, s2, v105
	v_mul_f32_e32 v104, s3, v104
	v_cvt_pk_bf16_f32 v105, v105, v1
	v_cvt_pk_bf16_f32 v104, v104, v1
	global_store_short v[172:173], v105, off
	global_store_short v[172:173], v104, off offset:2048
	v_lshl_add_u64 v[172:173], v[172:173], 0, s[8:9]
	v_readlane_b32 s2, v170, 16
	v_readlane_b32 s3, v170, 17
	s_nop 1
	v_mul_f32_e32 v103, s2, v103
	v_mul_f32_e32 v102, s3, v102
	v_cvt_pk_bf16_f32 v103, v103, v1
	v_cvt_pk_bf16_f32 v102, v102, v1
	global_store_short v[172:173], v103, off
	global_store_short v[172:173], v102, off offset:2048
	v_lshl_add_u64 v[172:173], v[172:173], 0, s[8:9]
	v_readlane_b32 s2, v170, 18
	v_readlane_b32 s3, v170, 19
	s_nop 1
	v_mul_f32_e32 v101, s2, v101
	v_mul_f32_e32 v100, s3, v100
	v_cvt_pk_bf16_f32 v101, v101, v1
	v_cvt_pk_bf16_f32 v100, v100, v1
	global_store_short v[172:173], v101, off
	global_store_short v[172:173], v100, off offset:2048
	v_lshl_add_u64 v[172:173], v[172:173], 0, s[8:9]
	v_readlane_b32 s2, v170, 20
	v_readlane_b32 s3, v170, 21
	s_nop 1
	v_mul_f32_e32 v99, s2, v99
	v_mul_f32_e32 v98, s3, v98
	v_cvt_pk_bf16_f32 v99, v99, v1
	v_cvt_pk_bf16_f32 v98, v98, v1
	global_store_short v[172:173], v99, off
	global_store_short v[172:173], v98, off offset:2048
	v_lshl_add_u64 v[172:173], v[172:173], 0, s[8:9]
	v_readlane_b32 s2, v170, 22
	v_readlane_b32 s3, v170, 23
	s_nop 1
	v_mul_f32_e32 v97, s2, v97
	v_mul_f32_e32 v96, s3, v96
	v_cvt_pk_bf16_f32 v97, v97, v1
	v_cvt_pk_bf16_f32 v96, v96, v1
	global_store_short v[172:173], v97, off
	global_store_short v[172:173], v96, off offset:2048
	v_lshl_add_u64 v[172:173], v[172:173], 0, s[8:9]
	v_readlane_b32 s2, v170, 24
	v_readlane_b32 s3, v170, 25
	s_nop 1
	v_mul_f32_e32 v13, s2, v13
	v_mul_f32_e32 v12, s3, v12
	v_cvt_pk_bf16_f32 v13, v13, v1
	v_cvt_pk_bf16_f32 v12, v12, v1
	global_store_short v[172:173], v13, off
	global_store_short v[172:173], v12, off offset:2048
	v_lshl_add_u64 v[172:173], v[172:173], 0, s[8:9]
	v_readlane_b32 s2, v170, 26
	v_readlane_b32 s3, v170, 27
	s_nop 1
	v_mul_f32_e32 v11, s2, v11
	v_mul_f32_e32 v10, s3, v10
	v_cvt_pk_bf16_f32 v11, v11, v1
	v_cvt_pk_bf16_f32 v10, v10, v1
	global_store_short v[172:173], v11, off
	global_store_short v[172:173], v10, off offset:2048
	v_lshl_add_u64 v[172:173], v[172:173], 0, s[8:9]
	v_readlane_b32 s2, v170, 28
	v_readlane_b32 s3, v170, 29
	s_nop 1
	v_mul_f32_e32 v9, s2, v9
	v_mul_f32_e32 v8, s3, v8
	v_cvt_pk_bf16_f32 v9, v9, v1
	v_cvt_pk_bf16_f32 v8, v8, v1
	global_store_short v[172:173], v9, off
	global_store_short v[172:173], v8, off offset:2048
	v_lshl_add_u64 v[172:173], v[172:173], 0, s[8:9]
	v_readlane_b32 s2, v170, 30
	v_readlane_b32 s3, v170, 31
	s_nop 1
	v_mul_f32_e32 v7, s2, v7
	v_mul_f32_e32 v6, s3, v6
	v_cvt_pk_bf16_f32 v7, v7, v1
	v_cvt_pk_bf16_f32 v6, v6, v1
	global_store_short v[172:173], v7, off
	global_store_short v[172:173], v6, off offset:2048
	s_add_i32 s4, s4, s5
	s_sub_i32 s12, s12, s13
	s_cmpk_lt_i32 s4, 0x500
	s_barrier
	s_cbranch_scc0 .LBB0_711
